# second-half partial/bonus loads issued at the tile latch for later second-half tiles
# speedup vs baseline: 1.0013x; 1.0013x over previous
.LBB0_406:
	s_or_b64 exec, exec, s[16:17]
	s_waitcnt vmcnt(0)
	v_mad_u64_u32 v[4:5], s[0:1], v0, s95, v[168:169]
	v_mov_b32_e32 v0, v5
	v_mad_u64_u32 v[0:1], s[0:1], v1, s95, v[0:1]
	v_mov_b32_e32 v5, v0
	global_load_dwordx4 v[24:27], v[4:5], off
	global_load_dwordx4 v[16:19], v[4:5], off offset:64
	global_load_dwordx4 v[28:31], v[4:5], off offset:512
	global_load_dwordx4 v[20:23], v[4:5], off offset:576
	global_load_dwordx4 v[8:11], v[4:5], off offset:128
	global_load_dwordx4 v[0:3], v[4:5], off offset:192
	global_load_dwordx4 v[12:15], v[4:5], off offset:640
	s_nop 0
	global_load_dwordx4 v[4:7], v[4:5], off offset:704
	s_add_i32 s88, s88, 1
	s_add_u32 s90, s90, -8
	s_addc_u32 s91, s91, -1
	s_add_u32 s18, s18, 8
	s_addc_u32 s19, s19, 0
	s_add_i32 s22, s22, 2
	s_cmp_eq_u32 s25, s77
	s_mov_b32 s25, s72
	v_add_u32_e32 v64, s90, v126
	v_mov_b32_e32 v129, s19
	v_add_u32_e32 v128, -9, v64
	v_cndmask_b32_e64 v131, 0, v129, s[4:5]
	v_mov_b32_e32 v129, s18
	v_cndmask_b32_e64 v128, v128, v175, s[4:5]
	v_cndmask_b32_e64 v130, 0, v129, s[4:5]
	v_lshl_add_u64 v[220:221], v[130:131], 0, s[92:93]
	v_ashrrev_i32_e32 v129, 31, v128
	v_lshl_add_u64 v[128:129], v[220:221], 0, v[128:129]
	v_lshlrev_b64 v[128:129], 13, v[128:129]
	v_or_b32_e32 v128, v128, v143
	v_lshl_add_u64 v[222:223], s[60:61], 0, v[128:129]
	v_lshl_add_u64 v[224:225], s[62:63], 0, v[128:129]
	v_lshl_add_u64 v[226:227], s[64:65], 0, v[128:129]
	v_add_u32_e32 v128, -10, v64
	v_cndmask_b32_e64 v128, v128, v178, s[4:5]
	v_ashrrev_i32_e32 v129, 31, v128
	v_lshl_add_u64 v[128:129], v[220:221], 0, v[128:129]
	v_lshlrev_b64 v[128:129], 13, v[128:129]
	v_or_b32_e32 v128, v128, v143
	v_lshl_add_u64 v[228:229], s[60:61], 0, v[128:129]
	v_lshl_add_u64 v[230:231], s[62:63], 0, v[128:129]
	v_lshl_add_u64 v[232:233], s[64:65], 0, v[128:129]
	v_add_u32_e32 v128, -11, v64
	v_cndmask_b32_e64 v128, v128, v180, s[4:5]
	v_ashrrev_i32_e32 v129, 31, v128
	v_lshl_add_u64 v[128:129], v[220:221], 0, v[128:129]
	v_lshlrev_b64 v[128:129], 13, v[128:129]
	v_or_b32_e32 v128, v128, v143
	v_add_u32_e32 v64, -12, v64
	v_lshl_add_u64 v[234:235], s[60:61], 0, v[128:129]
	v_lshl_add_u64 v[236:237], s[62:63], 0, v[128:129]
	v_lshl_add_u64 v[238:239], s[64:65], 0, v[128:129]
	v_cndmask_b32_e64 v128, v64, v182, s[4:5]
	v_ashrrev_i32_e32 v129, 31, v128
	v_lshl_add_u64 v[128:129], v[220:221], 0, v[128:129]
	v_lshlrev_b64 v[128:129], 13, v[128:129]
	v_or_b32_e32 v128, v128, v143
	v_lshl_add_u64 v[242:243], s[64:65], 0, v[128:129]
	global_load_ushort v82, v[232:233], off
	global_load_ushort v83, v[238:239], off
	v_lshl_add_u64 v[220:221], s[60:61], 0, v[128:129]
	v_lshl_add_u64 v[240:241], s[62:63], 0, v[128:129]
	global_load_ushort v84, v[242:243], off
	global_load_ushort v85, v[232:233], off offset:32
	global_load_ushort v86, v[238:239], off offset:32
	global_load_ushort v87, v[242:243], off offset:32
	s_nop 0
	global_load_ushort v88, v[222:223], off
	global_load_ushort v89, v[224:225], off
	global_load_ushort v90, v[226:227], off
	global_load_ushort v91, v[228:229], off
	global_load_ushort v92, v[230:231], off
	global_load_ushort v93, v[234:235], off
	global_load_ushort v94, v[236:237], off
	global_load_ushort v95, v[220:221], off
	global_load_ushort v96, v[240:241], off
	global_load_ushort v97, v[222:223], off offset:32
	s_nop 0
	global_load_ushort v98, v[224:225], off offset:32
	s_nop 0
	global_load_ushort v99, v[226:227], off offset:32
	s_nop 0
	global_load_ushort v100, v[228:229], off offset:32
	global_load_ushort v101, v[230:231], off offset:32
	s_nop 0
	global_load_ushort v102, v[234:235], off offset:32
	global_load_ushort v103, v[236:237], off offset:32
	global_load_ushort v104, v[220:221], off offset:32
	global_load_ushort v105, v[240:241], off offset:32
	s_cselect_b32 s20, 1, 0
	s_cmp_eq_u32 s90, 0
	s_cbranch_scc1 .Llp_skip
	s_add_i32 s2, s29, 1
	s_cmp_gt_u32 s25, s2
	s_cbranch_scc0 .Llp_skip
	s_add_i32 s30, s88, -3
	s_lshl_b64 s[0:1], s[30:31], 3
	s_add_u32 s0, s0, s92
	s_addc_u32 s1, s1, s93
	s_add_u32 s2, s23, s90
	s_addc_u32 s3, s24, s91
	s_add_u32 s2, s2, 7
	s_addc_u32 s3, s3, 0
	v_mov_b32_e32 v32, s0
	v_mov_b32_e32 v33, s1
	v_mov_b32_e32 v34, s2
	v_mov_b32_e32 v35, s3
	v_cndmask_b32_e64 v32, v32, v34, s[6:7]
	v_cndmask_b32_e64 v33, v33, v35, s[6:7]
	v_lshlrev_b64 v[34:35], 13, v[32:33]
	v_lshlrev_b64 v[36:37], 8, v[32:33]
	v_lshl_add_u64 v[226:227], v[118:119], 0, v[34:35]
	v_lshl_add_u64 v[36:37], v[120:121], 0, v[36:37]
	v_mov_b32_e32 v38, 0x2000
	v_mov_b32_e32 v39, 0xffffe000
	v_cndmask_b32_e64 v228, v38, v39, s[6:7]
	v_cndmask_b32_e64 v229, 0, -1, s[6:7]
	v_mov_b32_e32 v38, 0x100
	v_mov_b32_e32 v39, 0xffffff00
	v_cndmask_b32_e64 v40, v38, v39, s[6:7]
	v_mov_b32_e32 v41, v229
	v_mov_b32_e32 v34, v226
	v_mov_b32_e32 v35, v227
	global_load_ushort v204, v[34:35], off
	global_load_dword v212, v[36:37], off
	v_lshl_add_u64 v[34:35], v[34:35], 0, v[228:229]
	v_lshl_add_u64 v[36:37], v[36:37], 0, v[40:41]
	global_load_ushort v205, v[34:35], off
	global_load_dword v213, v[36:37], off
	v_lshl_add_u64 v[34:35], v[34:35], 0, v[228:229]
	v_lshl_add_u64 v[36:37], v[36:37], 0, v[40:41]
	global_load_ushort v206, v[34:35], off
	global_load_dword v214, v[36:37], off
	v_lshl_add_u64 v[34:35], v[34:35], 0, v[228:229]
	v_lshl_add_u64 v[36:37], v[36:37], 0, v[40:41]
	global_load_ushort v207, v[34:35], off
	global_load_dword v215, v[36:37], off
	v_lshl_add_u64 v[34:35], v[34:35], 0, v[228:229]
	v_lshl_add_u64 v[36:37], v[36:37], 0, v[40:41]
	global_load_ushort v208, v[34:35], off
	global_load_dword v216, v[36:37], off
	v_lshl_add_u64 v[34:35], v[34:35], 0, v[228:229]
	v_lshl_add_u64 v[36:37], v[36:37], 0, v[40:41]
	global_load_ushort v209, v[34:35], off
	global_load_dword v217, v[36:37], off
	v_lshl_add_u64 v[34:35], v[34:35], 0, v[228:229]
	v_lshl_add_u64 v[36:37], v[36:37], 0, v[40:41]
	global_load_ushort v210, v[34:35], off
	global_load_dword v218, v[36:37], off
	v_lshl_add_u64 v[34:35], v[34:35], 0, v[228:229]
	v_lshl_add_u64 v[36:37], v[36:37], 0, v[40:41]
	global_load_ushort v211, v[34:35], off
	global_load_dword v219, v[36:37], off
.Llp_skip:
	s_cmp_lg_u32 s20, 0
	s_waitcnt lgkmcnt(0)
	s_barrier
	s_cbranch_scc1 .LBB0_375
.LBB0_407:
	s_add_i32 s30, s88, -3
	s_cmp_lg_u32 s90, 0
	s_cselect_b64 s[16:17], -1, 0
	s_cmp_eq_u32 s90, 0
	s_cselect_b64 s[0:1], -1, 0
	s_cmp_gt_u32 s25, s29
	s_cselect_b64 s[96:97], -1, 0
	s_cmp_le_u32 s25, s29
	s_cselect_b64 s[2:3], -1, 0
	s_or_b64 s[0:1], s[0:1], s[2:3]
	s_and_b64 vcc, exec, s[0:1]
	s_cbranch_vccnz .LBB0_437
	s_add_i32 s2, s29, 1
	s_cmp_lg_u32 s25, s2
	s_cbranch_scc1 .LBB0_437
	s_lshl_b64 s[0:1], s[30:31], 3
	s_add_u32 s0, s0, s92
	s_addc_u32 s1, s1, s93
	s_add_u32 s2, s23, s90
	s_addc_u32 s3, s24, s91
	s_add_u32 s2, s2, 7
	s_addc_u32 s3, s3, 0
	v_mov_b32_e32 v32, s0
	v_mov_b32_e32 v33, s1
	v_mov_b32_e32 v34, s2
	v_mov_b32_e32 v35, s3
	v_cndmask_b32_e64 v32, v32, v34, s[6:7]
	v_cndmask_b32_e64 v33, v33, v35, s[6:7]
	v_lshlrev_b64 v[34:35], 13, v[32:33]
	v_lshlrev_b64 v[36:37], 8, v[32:33]
	v_lshl_add_u64 v[226:227], v[118:119], 0, v[34:35]
	v_lshl_add_u64 v[36:37], v[120:121], 0, v[36:37]
	v_mov_b32_e32 v38, 0x2000
	v_mov_b32_e32 v39, 0xffffe000
	v_cndmask_b32_e64 v228, v38, v39, s[6:7]
	v_cndmask_b32_e64 v229, 0, -1, s[6:7]
	v_mov_b32_e32 v38, 0x100
	v_mov_b32_e32 v39, 0xffffff00
	v_cndmask_b32_e64 v40, v38, v39, s[6:7]
	v_mov_b32_e32 v41, v229
	v_mov_b32_e32 v34, v226
	v_mov_b32_e32 v35, v227
	global_load_ushort v204, v[34:35], off
	global_load_dword v212, v[36:37], off
	v_lshl_add_u64 v[34:35], v[34:35], 0, v[228:229]
	v_lshl_add_u64 v[36:37], v[36:37], 0, v[40:41]
	global_load_ushort v205, v[34:35], off
	global_load_dword v213, v[36:37], off
	v_lshl_add_u64 v[34:35], v[34:35], 0, v[228:229]
	v_lshl_add_u64 v[36:37], v[36:37], 0, v[40:41]
	global_load_ushort v206, v[34:35], off
	global_load_dword v214, v[36:37], off
	v_lshl_add_u64 v[34:35], v[34:35], 0, v[228:229]
	v_lshl_add_u64 v[36:37], v[36:37], 0, v[40:41]
	global_load_ushort v207, v[34:35], off
	global_load_dword v215, v[36:37], off
	v_lshl_add_u64 v[34:35], v[34:35], 0, v[228:229]
	v_lshl_add_u64 v[36:37], v[36:37], 0, v[40:41]
	global_load_ushort v208, v[34:35], off
	global_load_dword v216, v[36:37], off
	v_lshl_add_u64 v[34:35], v[34:35], 0, v[228:229]
	v_lshl_add_u64 v[36:37], v[36:37], 0, v[40:41]
	global_load_ushort v209, v[34:35], off
	global_load_dword v217, v[36:37], off
	v_lshl_add_u64 v[34:35], v[34:35], 0, v[228:229]
	v_lshl_add_u64 v[36:37], v[36:37], 0, v[40:41]
	global_load_ushort v210, v[34:35], off
	global_load_dword v218, v[36:37], off
	v_lshl_add_u64 v[34:35], v[34:35], 0, v[228:229]
	v_lshl_add_u64 v[36:37], v[36:37], 0, v[40:41]
	global_load_ushort v211, v[34:35], off
	global_load_dword v219, v[36:37], off
